# attention loops: LDS tile store + global prefetch moved to the loop top after the first K reads; two-level grid barrier for syncs 2..13; down-proj epilogue loads batched
# speedup vs baseline: 1.0171x; 1.0108x over previous
; #define LSTORE(buf_, KR, VR) do { _Pragma("unroll") for (int i = 0; i < KCH; ++i) if (krow_[i] < 64) *(u32x4*)(sK + (buf_) * 64 * KROW + krow_[i] * KROW + kcol_[i]) = KR[i]; \
;     u16* d_ = sV + (buf_) * 64 * VROW + vrow * VROW + (vcol >> 4) * 16 + ((vcol >> 3) & 1) * 4; u32x2 lo_ = {VR.x, VR.y}, hi_ = {VR.z, VR.w}; *(u32x2*)d_ = lo_; *(u32x2*)(d_ + 8) = hi_; } while (0)
; template <int DQ>
; DI void attn_dense_item(const u16* __restrict__ Q, int qh, const u16* __restrict__ Kp, int HK, int kh, const u16* __restrict__ Vt,
;                         int S, int s0, int qblk, u16* __restrict__ MER, int ocol, float* __restrict__ ssqo, int slot, unsigned char* smem) {
;     ...
;     const int sb = (kt & 2), nb = sb ^ 2;
;     TILE_X2(sb, kt == 0); TILE_Y2(sb);
;     if (kt + 2 < nkt) { LSTORE(nb, krA, vrA); LSTORE(nb + 1, krB, vrB); }
.Lmla_B_ls:
	s_add_i32 s6, s14, -4
	s_and_b32 s6, s6, 2
	s_add_i32 s15, s14, -2
	s_cmp_ge_u32 s15, s23
	s_cbranch_scc1 .Lmla_B_312
	s_xor_b32 s16, s6, 2
	s_mul_i32 s6, s16, 0x3400
	s_add_i32 s17, s6, 0
	v_add3_u32 v50, s17, v173, v192
	s_and_saveexec_b64 s[6:7], s[0:1]
	s_cbranch_execz .Lmla_B_305
	s_waitcnt vmcnt(2)
	ds_write_b128 v50, v[138:141]

.Lmla_B_319:
	s_or_b64 exec, exec, s[6:7]
	s_and_saveexec_b64 s[6:7], s[4:5]
	s_cbranch_execz .Lmla_B_298
	v_add_co_u32_e32 v50, vcc, 0x2ef5e000, v52
	s_nop 1
	v_addc_co_u32_e32 v51, vcc, 0, v53, vcc
	global_load_dwordx4 v[150:153], v[50:51], off
	s_branch .Lmla_B_298
.Lmla_B_298:
	s_or_b64 exec, exec, s[6:7]
	v_add_co_u32_e32 v50, vcc, 0x35aee000, v54
	s_nop 1
	v_addc_co_u32_e32 v51, vcc, 0, v55, vcc
	global_load_dwordx4 v[158:161], v[50:51], off
.Lmla_B_ls_end:
	s_add_i32 s6, s14, -4
	s_and_b32 s6, s6, 2
	s_mul_i32 s7, s6, 0x2400
	v_add_f32_e32 v201, v74, v201
	v_add_f32_e32 v247, v75, v76
	v_add_f32_e32 v201, v77, v201
	v_add_f32_e32 v247, v78, v247
	v_add_f32_e32 v201, v79, v201
	v_add_f32_e32 v247, v80, v247
	v_add_f32_e32 v201, v81, v201
	v_add_f32_e32 v247, v82, v247
	v_add_f32_e32 v201, v83, v201
	v_add_f32_e32 v247, v84, v247
	v_add_f32_e32 v201, v85, v201
	v_add_f32_e32 v247, v86, v247
	v_add_f32_e32 v201, v87, v201
	v_add_f32_e32 v247, v88, v247
	s_waitcnt lgkmcnt(6)
	v_mfma_f32_32x32x16_bf16 v[50:65], v[226:229], v[114:117], v[34:49]
	ds_read_b128 v[226:229], v0 offset:6688
	v_add_f32_e32 v201, v89, v201
	v_add_f32_e32 v247, v90, v247
	v_add_f32_e32 v201, v91, v201
	v_add_f32_e32 v247, v92, v247
	v_add_f32_e32 v201, v93, v201
	s_waitcnt lgkmcnt(6)
	v_mfma_f32_32x32x16_bf16 v[50:65], v[230:233], v[118:121], v[50:65]
	ds_read_b128 v[230:233], v0 offset:6720
	v_add_f32_e32 v247, v94, v247
	v_add_f32_e32 v201, v95, v201
	v_add_f32_e32 v247, v96, v247
	v_add_f32_e32 v201, v97, v201
	v_add_f32_e32 v247, v98, v247
	s_waitcnt lgkmcnt(6)
	v_mfma_f32_32x32x16_bf16 v[50:65], v[234:237], v[122:125], v[50:65]
	ds_read_b128 v[234:237], v0 offset:6752
	v_add_f32_e32 v201, v99, v201
	v_add_f32_e32 v247, v100, v247
	v_add_f32_e32 v201, v101, v201
	v_add_f32_e32 v247, v102, v247
	s_waitcnt lgkmcnt(6)
	v_mfma_f32_32x32x16_bf16 v[50:65], v[238:241], v[126:129], v[50:65]
	ds_read_b128 v[238:241], v0 offset:6784
	v_add_f32_e32 v201, v103, v201
	v_add_f32_e32 v247, v104, v247
	v_add_f32_e32 v201, v105, v201
	v_add_f32_e32 v247, v106, v247
	s_waitcnt lgkmcnt(6)
	v_mfma_f32_32x32x16_bf16 v[50:65], v[242:245], v[130:133], v[50:65]
	ds_read_b128 v[242:245], v0 offset:6816
	v_add_f32_e32 v201, v107, v201
	v_add_f32_e32 v247, v108, v247
	v_add_f32_e32 v201, v109, v201
	v_add_f32_e32 v247, v110, v247
	s_waitcnt lgkmcnt(6)
	v_mfma_f32_32x32x16_bf16 v[50:65], v[162:165], v[134:137], v[50:65]
	ds_read_b128 v[162:165], v225
	v_add_f32_e32 v201, v111, v201
	v_add_f32_e32 v247, v112, v247
	v_add_f32_e32 v201, v113, v201
	v_add_f32_e32 v247, v246, v247
	s_waitcnt lgkmcnt(6)
	v_mfma_f32_32x32x16_bf16 v[66:81], v[166:169], v[114:117], v[34:49]
	ds_read_b128 v[166:169], v225 offset:32
	v_add_f32_e32 v201, v202, v201
	v_add_f32_e32 v247, v203, v247
	v_add_f32_e32 v201, v204, v201
	v_add_f32_e32 v247, v205, v247
	s_waitcnt lgkmcnt(6)
	v_mfma_f32_32x32x16_bf16 v[66:81], v[226:229], v[118:121], v[66:81]
	ds_read_b128 v[226:229], v225 offset:64
	v_add_f32_e32 v201, v206, v201
	v_add_f32_e32 v247, v207, v247
	v_add_f32_e32 v201, v208, v201
	v_add_f32_e32 v247, v209, v247
	s_waitcnt lgkmcnt(6)
	v_mfma_f32_32x32x16_bf16 v[66:81], v[230:233], v[122:125], v[66:81]
	ds_read_b128 v[230:233], v225 offset:96
	v_add_f32_e32 v201, v210, v201
	v_add_f32_e32 v247, v211, v247
	v_add_f32_e32 v201, v212, v201
	v_add_f32_e32 v247, v213, v247
	v_max3_f32 v0, v50, v51, v52
	v_max3_f32 v0, v0, v53, v54
	s_waitcnt lgkmcnt(6)
	v_mfma_f32_32x32x16_bf16 v[66:81], v[234:237], v[126:129], v[66:81]
	ds_read_b128 v[234:237], v225 offset:128
	v_add_f32_e32 v201, v214, v201
	v_add_f32_e32 v247, v215, v247
	v_add_f32_e32 v201, v216, v201
	v_add_f32_e32 v247, v217, v247
	v_max3_f32 v0, v0, v55, v56
	v_max3_f32 v0, v0, v57, v58
	s_waitcnt lgkmcnt(6)
	v_mfma_f32_32x32x16_bf16 v[66:81], v[238:241], v[130:133], v[66:81]
	ds_read_b128 v[238:241], v225 offset:160
	v_add_f32_e32 v201, v218, v201
	v_add_f32_e32 v247, v219, v247
	v_add_f32_e32 v201, v220, v201
	v_add_f32_e32 v247, v221, v247
	v_max3_f32 v0, v0, v59, v60
	v_max3_f32 v0, v0, v61, v62
	s_waitcnt lgkmcnt(6)
	v_mfma_f32_32x32x16_bf16 v[66:81], v[242:245], v[134:137], v[66:81]
	ds_read_b128 v[242:245], v225 offset:6656
	v_add_f32_e32 v201, v222, v201
	v_add_f32_e32 v247, v223, v247
	v_add_f32_e32 v201, v224, v201
	v_add_f32_e32 v201, v247, v201
	v_max3_f32 v0, v0, v63, v64
	v_max3_f32 v0, v0, v65, v65
	s_waitcnt lgkmcnt(6)
	v_mfma_f32_32x32x16_bf16 v[82:97], v[162:165], v[114:117], v[34:49]
	ds_read_b128 v[162:165], v225 offset:6688
	s_waitcnt lgkmcnt(6)
	v_mfma_f32_32x32x16_bf16 v[82:97], v[166:169], v[118:121], v[82:97]
	ds_read_b128 v[166:169], v225 offset:6720
	v_add3_u32 v247, v198, s7, v200
	s_waitcnt lgkmcnt(6)
	v_mfma_f32_32x32x16_bf16 v[82:97], v[226:229], v[122:125], v[82:97]
	ds_read_b128 v[226:229], v225 offset:6752
	v_max3_f32 v0, v0, v66, v67
	v_max3_f32 v0, v0, v68, v69
	s_waitcnt lgkmcnt(6)
	v_mfma_f32_32x32x16_bf16 v[82:97], v[230:233], v[126:129], v[82:97]
	ds_read_b128 v[230:233], v225 offset:6784
	v_max3_f32 v0, v0, v70, v71
	v_max3_f32 v0, v0, v72, v73
	s_waitcnt lgkmcnt(6)
	v_mfma_f32_32x32x16_bf16 v[82:97], v[234:237], v[130:133], v[82:97]
	ds_read_b128 v[234:237], v225 offset:6816
	v_max3_f32 v0, v0, v74, v75
	v_max3_f32 v0, v0, v76, v77
	s_waitcnt lgkmcnt(6)
	v_mfma_f32_32x32x16_bf16 v[82:97], v[238:241], v[134:137], v[82:97]
	ds_read_b128 v[238:241], v247 offset:53248
	v_max3_f32 v0, v0, v78, v79
	v_max3_f32 v0, v0, v80, v81
	s_waitcnt lgkmcnt(6)
	v_mfma_f32_32x32x16_bf16 v[98:113], v[242:245], v[114:117], v[34:49]
	ds_read_b128 v[242:245], v247 offset:57856
	s_waitcnt lgkmcnt(6)
	v_mfma_f32_32x32x16_bf16 v[98:113], v[162:165], v[118:121], v[98:113]
	s_waitcnt lgkmcnt(5)
	v_mfma_f32_32x32x16_bf16 v[98:113], v[166:169], v[122:125], v[98:113]
	s_waitcnt lgkmcnt(4)
	v_mfma_f32_32x32x16_bf16 v[98:113], v[226:229], v[126:129], v[98:113]
	ds_read_b128 v[226:229], v247 offset:53280
	s_waitcnt lgkmcnt(4)
	v_mfma_f32_32x32x16_bf16 v[98:113], v[230:233], v[130:133], v[98:113]
	ds_read_b128 v[230:233], v247 offset:57888
	s_waitcnt lgkmcnt(4)
	v_mfma_f32_32x32x16_bf16 v[98:113], v[234:237], v[134:137], v[98:113]
	ds_read_b128 v[234:237], v247 offset:53312
	v_max3_f32 v0, v0, v82, v83
	v_max3_f32 v0, v0, v84, v85
	v_max3_f32 v0, v0, v86, v87
	v_max3_f32 v0, v0, v88, v89
	v_max3_f32 v0, v0, v90, v91
	v_max3_f32 v0, v0, v92, v93
	v_max3_f32 v0, v0, v94, v95
	v_max3_f32 v0, v0, v96, v97
	s_nop 4
	v_max3_f32 v0, v0, v98, v99
	v_max3_f32 v0, v0, v100, v101
	v_max3_f32 v0, v0, v102, v103
	v_max3_f32 v0, v0, v104, v105
	v_max3_f32 v0, v0, v106, v107
	v_max3_f32 v0, v0, v108, v109
	v_max3_f32 v0, v0, v110, v111
	v_max3_f32 v0, v0, v112, v113
	v_mov_b32_e32 v162, v0
	s_nop 1
	v_permlane32_swap_b32_e32 v0, v162
	v_max_f32_e32 v162, v162, v162
	v_max_f32_e32 v0, v0, v0
	v_max_f32_e32 v0, v0, v162
	v_cmp_lt_f32_e32 vcc, s50, v0
	s_cbranch_vccz .LBB0_302
	v_max_f32_e32 v0, v0, v0
	v_max_f32_e32 v0, 0, v0
	v_exp_f32_e64 v162, -v0
	v_pk_add_f32 v[50:51], v[50:51], v[0:1] op_sel_hi:[1,0] neg_lo:[0,1] neg_hi:[0,1]
	v_pk_add_f32 v[66:67], v[66:67], v[0:1] op_sel_hi:[1,0] neg_lo:[0,1] neg_hi:[0,1]
	v_pk_add_f32 v[82:83], v[82:83], v[0:1] op_sel_hi:[1,0] neg_lo:[0,1] neg_hi:[0,1]
	v_mul_f32_e32 v201, v201, v162
	v_pk_mul_f32 v[16:17], v[16:17], v[162:163] op_sel_hi:[1,0]
	v_pk_mul_f32 v[14:15], v[14:15], v[162:163] op_sel_hi:[1,0]
	v_pk_mul_f32 v[12:13], v[12:13], v[162:163] op_sel_hi:[1,0]
	v_pk_mul_f32 v[10:11], v[10:11], v[162:163] op_sel_hi:[1,0]
	v_pk_mul_f32 v[8:9], v[8:9], v[162:163] op_sel_hi:[1,0]
	v_pk_mul_f32 v[6:7], v[6:7], v[162:163] op_sel_hi:[1,0]
	v_pk_mul_f32 v[4:5], v[4:5], v[162:163] op_sel_hi:[1,0]
	v_pk_mul_f32 v[2:3], v[2:3], v[162:163] op_sel_hi:[1,0]
	v_pk_mul_f32 v[32:33], v[32:33], v[162:163] op_sel_hi:[1,0]
	v_pk_mul_f32 v[30:31], v[30:31], v[162:163] op_sel_hi:[1,0]
	v_pk_mul_f32 v[28:29], v[28:29], v[162:163] op_sel_hi:[1,0]
	v_pk_mul_f32 v[26:27], v[26:27], v[162:163] op_sel_hi:[1,0]
	v_pk_mul_f32 v[24:25], v[24:25], v[162:163] op_sel_hi:[1,0]
	v_pk_mul_f32 v[22:23], v[22:23], v[162:163] op_sel_hi:[1,0]
	v_pk_mul_f32 v[20:21], v[20:21], v[162:163] op_sel_hi:[1,0]
	v_pk_mul_f32 v[18:19], v[18:19], v[162:163] op_sel_hi:[1,0]
	v_pk_add_f32 v[98:99], v[98:99], v[0:1] op_sel_hi:[1,0] neg_lo:[0,1] neg_hi:[0,1]
	v_pk_add_f32 v[52:53], v[52:53], v[0:1] op_sel_hi:[1,0] neg_lo:[0,1] neg_hi:[0,1]
	v_pk_add_f32 v[68:69], v[68:69], v[0:1] op_sel_hi:[1,0] neg_lo:[0,1] neg_hi:[0,1]
	v_pk_add_f32 v[84:85], v[84:85], v[0:1] op_sel_hi:[1,0] neg_lo:[0,1] neg_hi:[0,1]
	v_pk_add_f32 v[100:101], v[100:101], v[0:1] op_sel_hi:[1,0] neg_lo:[0,1] neg_hi:[0,1]
	v_pk_add_f32 v[54:55], v[54:55], v[0:1] op_sel_hi:[1,0] neg_lo:[0,1] neg_hi:[0,1]
	v_pk_add_f32 v[70:71], v[70:71], v[0:1] op_sel_hi:[1,0] neg_lo:[0,1] neg_hi:[0,1]
	v_pk_add_f32 v[86:87], v[86:87], v[0:1] op_sel_hi:[1,0] neg_lo:[0,1] neg_hi:[0,1]
	v_pk_add_f32 v[102:103], v[102:103], v[0:1] op_sel_hi:[1,0] neg_lo:[0,1] neg_hi:[0,1]
	v_pk_add_f32 v[56:57], v[56:57], v[0:1] op_sel_hi:[1,0] neg_lo:[0,1] neg_hi:[0,1]
	v_pk_add_f32 v[72:73], v[72:73], v[0:1] op_sel_hi:[1,0] neg_lo:[0,1] neg_hi:[0,1]
	v_pk_add_f32 v[88:89], v[88:89], v[0:1] op_sel_hi:[1,0] neg_lo:[0,1] neg_hi:[0,1]
	v_pk_add_f32 v[104:105], v[104:105], v[0:1] op_sel_hi:[1,0] neg_lo:[0,1] neg_hi:[0,1]
	v_pk_add_f32 v[58:59], v[58:59], v[0:1] op_sel_hi:[1,0] neg_lo:[0,1] neg_hi:[0,1]
	v_pk_add_f32 v[74:75], v[74:75], v[0:1] op_sel_hi:[1,0] neg_lo:[0,1] neg_hi:[0,1]
	v_pk_add_f32 v[90:91], v[90:91], v[0:1] op_sel_hi:[1,0] neg_lo:[0,1] neg_hi:[0,1]
	v_pk_add_f32 v[106:107], v[106:107], v[0:1] op_sel_hi:[1,0] neg_lo:[0,1] neg_hi:[0,1]
	v_pk_add_f32 v[60:61], v[60:61], v[0:1] op_sel_hi:[1,0] neg_lo:[0,1] neg_hi:[0,1]
	v_pk_add_f32 v[76:77], v[76:77], v[0:1] op_sel_hi:[1,0] neg_lo:[0,1] neg_hi:[0,1]
	v_pk_add_f32 v[92:93], v[92:93], v[0:1] op_sel_hi:[1,0] neg_lo:[0,1] neg_hi:[0,1]
	v_pk_add_f32 v[108:109], v[108:109], v[0:1] op_sel_hi:[1,0] neg_lo:[0,1] neg_hi:[0,1]
	v_pk_add_f32 v[62:63], v[62:63], v[0:1] op_sel_hi:[1,0] neg_lo:[0,1] neg_hi:[0,1]
	v_pk_add_f32 v[78:79], v[78:79], v[0:1] op_sel_hi:[1,0] neg_lo:[0,1] neg_hi:[0,1]
	v_pk_add_f32 v[94:95], v[94:95], v[0:1] op_sel_hi:[1,0] neg_lo:[0,1] neg_hi:[0,1]
	v_pk_add_f32 v[110:111], v[110:111], v[0:1] op_sel_hi:[1,0] neg_lo:[0,1] neg_hi:[0,1]
	v_pk_add_f32 v[64:65], v[64:65], v[0:1] op_sel_hi:[1,0] neg_lo:[0,1] neg_hi:[0,1]
	v_pk_add_f32 v[80:81], v[80:81], v[0:1] op_sel_hi:[1,0] neg_lo:[0,1] neg_hi:[0,1]
	v_pk_add_f32 v[96:97], v[96:97], v[0:1] op_sel_hi:[1,0] neg_lo:[0,1] neg_hi:[0,1]
	v_pk_add_f32 v[112:113], v[112:113], v[0:1] op_sel_hi:[1,0] neg_lo:[0,1] neg_hi:[0,1]
	v_sub_f32_e32 v49, v49, v0
	v_sub_f32_e32 v48, v48, v0
	v_sub_f32_e32 v47, v47, v0
	v_sub_f32_e32 v46, v46, v0
	v_sub_f32_e32 v45, v45, v0
	v_sub_f32_e32 v44, v44, v0
	v_sub_f32_e32 v43, v43, v0
	v_sub_f32_e32 v42, v42, v0
	v_sub_f32_e32 v41, v41, v0
	v_sub_f32_e32 v40, v40, v0
	v_sub_f32_e32 v39, v39, v0
	v_sub_f32_e32 v38, v38, v0
	v_sub_f32_e32 v37, v37, v0
	v_sub_f32_e32 v36, v36, v0
	v_sub_f32_e32 v35, v35, v0
	v_sub_f32_e32 v34, v34, v0
; #define GLOAD(kt_, KR, VR) do { _Pragma("unroll") for (int i = 0; i < KCH; ++i) if (krow_[i] < 64) KR[i] = *(const u32x4*)(kbase + (size_t)((kt_) * 64 + krow_[i]) * HK * DQ + kcol_[i]); \
;     VR = *(const u32x4*)(vbase + (size_t)(kt_) * 4096 + vrow * 64 + vcol); } while (0)
; #define LSTORE(buf_, KR, VR) do { _Pragma("unroll") for (int i = 0; i < KCH; ++i) if (krow_[i] < 64) *(u32x4*)(sK + (buf_) * 64 * KROW + krow_[i] * KROW + kcol_[i]) = KR[i]; \
;     u16* d_ = sV + (buf_) * 64 * VROW + vrow * VROW + (vcol >> 4) * 16 + ((vcol >> 3) & 1) * 4; u32x2 lo_ = {VR.x, VR.y}, hi_ = {VR.z, VR.w}; *(u32x2*)d_ = lo_; *(u32x2*)(d_ + 8) = hi_; } while (0)
; #define PP_BAR asm volatile("s_waitcnt lgkmcnt(0)\n\ts_barrier" ::: "memory")
; template <int DQ>
; DI void attn_dense_item(const u16* __restrict__ Q, int qh, const u16* __restrict__ Kp, int HK, int kh, const u16* __restrict__ Vt,
;                         int S, int s0, int qblk, u16* __restrict__ MER, int ocol, float* __restrict__ ssqo, int slot, unsigned char* smem) {
;     ...
;   s16x8 pb[8];
;   for (int kt = 0; kt < nkt; kt += 2) {
;     const int sb = (kt & 2), nb = sb ^ 2;
;     TILE_X2(sb, kt == 0); TILE_Y2(sb);
;     if (kt + 2 < nkt) { LSTORE(nb, krA, vrA); LSTORE(nb + 1, krB, vrB); }
;     if (kt + 4 < nkt) { GLOAD(kt + 4, krA, vrA); GLOAD(kt + 5, krB, vrB); }
;     PP_BAR;
.LBB0_302:
	s_addk_i32 s7, 0x2400
	v_add3_u32 v0, v198, s7, v200
	v_exp_f32_e32 v246, v50
	v_exp_f32_e32 v202, v51
	v_exp_f32_e32 v203, v52
	v_exp_f32_e32 v204, v53
	v_exp_f32_e32 v205, v54
	v_exp_f32_e32 v206, v55
	v_exp_f32_e32 v207, v56
	v_exp_f32_e32 v208, v57
	v_cvt_pk_bf16_f32 v166, v246, v202
	v_cvt_pk_bf16_f32 v167, v203, v204
	v_cvt_pk_bf16_f32 v168, v205, v206
	v_cvt_pk_bf16_f32 v169, v207, v208
	v_exp_f32_e32 v209, v58
	v_exp_f32_e32 v210, v59
	s_waitcnt lgkmcnt(4)
	v_mfma_f32_32x32x16_bf16 v[18:33], v[238:241], v[166:169], v[18:33]
	ds_read_b128 v[238:241], v247 offset:57920
	v_exp_f32_e32 v211, v60
	v_exp_f32_e32 v212, v61
	v_exp_f32_e32 v213, v62
	v_exp_f32_e32 v214, v63
	v_exp_f32_e32 v215, v64
	v_exp_f32_e32 v216, v65
	s_waitcnt lgkmcnt(4)
	v_mfma_f32_32x32x16_bf16 v[2:17], v[242:245], v[166:169], v[2:17]
	ds_read_b128 v[242:245], v247 offset:53344
	v_cvt_pk_bf16_f32 v162, v209, v210
	v_cvt_pk_bf16_f32 v163, v211, v212
	v_cvt_pk_bf16_f32 v164, v213, v214
	v_cvt_pk_bf16_f32 v165, v215, v216
	v_exp_f32_e32 v217, v66
	v_exp_f32_e32 v218, v67
	s_waitcnt lgkmcnt(4)
	v_mfma_f32_32x32x16_bf16 v[18:33], v[226:229], v[162:165], v[18:33]
	ds_read_b128 v[226:229], v247 offset:57952
	v_exp_f32_e32 v219, v68
	v_exp_f32_e32 v220, v69
	v_exp_f32_e32 v221, v70
	v_exp_f32_e32 v222, v71
	v_exp_f32_e32 v223, v72
	v_exp_f32_e32 v224, v73
	v_cvt_pk_bf16_f32 v70, v217, v218
	s_waitcnt lgkmcnt(4)
	v_mfma_f32_32x32x16_bf16 v[2:17], v[230:233], v[162:165], v[2:17]
	ds_read_b128 v[230:233], v0 offset:53248
	v_cvt_pk_bf16_f32 v71, v219, v220
	v_cvt_pk_bf16_f32 v72, v221, v222
	v_cvt_pk_bf16_f32 v73, v223, v224
	v_exp_f32_e32 v74, v74
	v_exp_f32_e32 v75, v75
	v_exp_f32_e32 v76, v76
	s_waitcnt lgkmcnt(4)
	v_mfma_f32_32x32x16_bf16 v[18:33], v[234:237], v[70:73], v[18:33]
	ds_read_b128 v[234:237], v0 offset:57856
	v_exp_f32_e32 v77, v77
	v_exp_f32_e32 v78, v78
	v_exp_f32_e32 v79, v79
	v_exp_f32_e32 v80, v80
	v_exp_f32_e32 v81, v81
	v_cvt_pk_bf16_f32 v66, v74, v75
	s_waitcnt lgkmcnt(4)
	v_mfma_f32_32x32x16_bf16 v[2:17], v[238:241], v[70:73], v[2:17]
	ds_read_b128 v[238:241], v0 offset:53280
	v_cvt_pk_bf16_f32 v67, v76, v77
	v_cvt_pk_bf16_f32 v68, v78, v79
	v_cvt_pk_bf16_f32 v69, v80, v81
	v_exp_f32_e32 v82, v82
	v_exp_f32_e32 v83, v83
	s_waitcnt lgkmcnt(4)
	v_mfma_f32_32x32x16_bf16 v[18:33], v[242:245], v[66:69], v[18:33]
	ds_read_b128 v[242:245], v0 offset:57888
	v_exp_f32_e32 v84, v84
	v_exp_f32_e32 v85, v85
	v_exp_f32_e32 v86, v86
	v_exp_f32_e32 v87, v87
	v_exp_f32_e32 v88, v88
	v_exp_f32_e32 v89, v89
	s_waitcnt lgkmcnt(4)
	v_mfma_f32_32x32x16_bf16 v[2:17], v[226:229], v[66:69], v[2:17]
	ds_read_b128 v[226:229], v0 offset:53312
	v_cvt_pk_bf16_f32 v62, v82, v83
	v_cvt_pk_bf16_f32 v63, v84, v85
	v_cvt_pk_bf16_f32 v64, v86, v87
	v_cvt_pk_bf16_f32 v65, v88, v89
	v_exp_f32_e32 v90, v90
	v_exp_f32_e32 v91, v91
	s_waitcnt lgkmcnt(4)
	v_mfma_f32_32x32x16_bf16 v[18:33], v[230:233], v[62:65], v[18:33]
	ds_read_b128 v[230:233], v0 offset:57920
	v_exp_f32_e32 v92, v92
	v_exp_f32_e32 v93, v93
	v_exp_f32_e32 v94, v94
	v_exp_f32_e32 v95, v95
	v_exp_f32_e32 v96, v96
	v_exp_f32_e32 v97, v97
	s_waitcnt lgkmcnt(4)
	v_mfma_f32_32x32x16_bf16 v[2:17], v[234:237], v[62:65], v[2:17]
	ds_read_b128 v[234:237], v0 offset:53344
	v_cvt_pk_bf16_f32 v58, v90, v91
	v_cvt_pk_bf16_f32 v59, v92, v93
	v_cvt_pk_bf16_f32 v60, v94, v95
	v_cvt_pk_bf16_f32 v61, v96, v97
	v_exp_f32_e32 v98, v98
	v_exp_f32_e32 v99, v99
	s_waitcnt lgkmcnt(4)
	v_mfma_f32_32x32x16_bf16 v[18:33], v[238:241], v[58:61], v[18:33]
	ds_read_b128 v[238:241], v0 offset:57952
	v_exp_f32_e32 v100, v100
	v_exp_f32_e32 v101, v101
	v_exp_f32_e32 v102, v102
	v_exp_f32_e32 v103, v103
	v_exp_f32_e32 v104, v104
	v_exp_f32_e32 v105, v105
	v_cvt_pk_bf16_f32 v54, v98, v99
	s_waitcnt lgkmcnt(4)
	v_mfma_f32_32x32x16_bf16 v[2:17], v[242:245], v[58:61], v[2:17]
	v_cvt_pk_bf16_f32 v55, v100, v101
	v_cvt_pk_bf16_f32 v56, v102, v103
	v_cvt_pk_bf16_f32 v57, v104, v105
	v_exp_f32_e32 v106, v106
	v_exp_f32_e32 v107, v107
	v_exp_f32_e32 v108, v108
	s_waitcnt lgkmcnt(3)
	v_mfma_f32_32x32x16_bf16 v[18:33], v[226:229], v[54:57], v[18:33]
	v_exp_f32_e32 v109, v109
	v_exp_f32_e32 v110, v110
	v_exp_f32_e32 v111, v111
	v_exp_f32_e32 v112, v112
	v_exp_f32_e32 v113, v113
	v_cvt_pk_bf16_f32 v50, v106, v107
	s_waitcnt lgkmcnt(2)
	v_mfma_f32_32x32x16_bf16 v[2:17], v[230:233], v[54:57], v[2:17]
	v_cvt_pk_bf16_f32 v51, v108, v109
	v_cvt_pk_bf16_f32 v52, v110, v111
	v_cvt_pk_bf16_f32 v53, v112, v113
	s_add_i32 s15, s14, -2
	s_cmp_ge_u32 s15, s23
	s_waitcnt lgkmcnt(1)
	v_mfma_f32_32x32x16_bf16 v[18:33], v[234:237], v[50:53], v[18:33]
	s_waitcnt lgkmcnt(0)
	v_mfma_f32_32x32x16_bf16 v[2:17], v[238:241], v[50:53], v[2:17]
	s_branch .LBB0_299

; #define LSTORE(buf_, KR, VR) do { _Pragma("unroll") for (int i = 0; i < KCH; ++i) if (krow_[i] < 64) *(u32x4*)(sK + (buf_) * 64 * KROW + krow_[i] * KROW + kcol_[i]) = KR[i]; \
;     u16* d_ = sV + (buf_) * 64 * VROW + vrow * VROW + (vcol >> 4) * 16 + ((vcol >> 3) & 1) * 4; u32x2 lo_ = {VR.x, VR.y}, hi_ = {VR.z, VR.w}; *(u32x2*)d_ = lo_; *(u32x2*)(d_ + 8) = hi_; } while (0)
; template <int DQ>
; DI void attn_dense_item(const u16* __restrict__ Q, int qh, const u16* __restrict__ Kp, int HK, int kh, const u16* __restrict__ Vt,
;                         int S, int s0, int qblk, u16* __restrict__ MER, int ocol, float* __restrict__ ssqo, int slot, unsigned char* smem) {
;     ...
;     const int sb = (kt & 2), nb = sb ^ 2;
;     TILE_X2(sb, kt == 0); TILE_Y2(sb);
;     if (kt + 2 < nkt) { LSTORE(nb, krA, vrA); LSTORE(nb + 1, krB, vrB); }
.Lgqa_B_ls:
	s_add_i32 s4, s12, -4
	s_and_b32 s4, s4, 2
	s_add_i32 s13, s12, -2
	s_cmp_ge_u32 s13, s23
	s_cbranch_scc1 .Lgqa_B_356
	s_xor_b32 s14, s4, 2
	s_mulk_i32 s14, 0x2400
	s_and_saveexec_b64 s[4:5], s[0:1]
	s_cbranch_execz .Lgqa_B_353
	v_add_u32_e32 v243, s14, v164
	s_waitcnt vmcnt(2)
	ds_write_b128 v243, v[130:133]
.Lgqa_B_353:
	s_or_b64 exec, exec, s[4:5]
	s_add_i32 s14, s14, 0
	v_lshl_add_u32 v243, v160, 1, s14
	v_add3_u32 v243, v243, v161, v162
	v_add_u32_e32 v50, 0x9000, v243
	s_waitcnt vmcnt(1)
	ds_write2_b64 v50, v[138:139], v[140:141] offset1:2
	s_and_saveexec_b64 s[4:5], s[0:1]
	v_add3_u32 v50, s14, v159, v153
	ds_write_b128 v50, v[134:137] offset:9216
	s_or_b64 exec, exec, s[4:5]
	v_add_u32_e32 v243, 0xb000, v243
	s_waitcnt vmcnt(0)
	ds_write2_b64 v243, v[142:143], v[144:145] offset0:128 offset1:130

.Lgqa_B_359:
	s_or_b64 exec, exec, s[4:5]
	v_lshl_add_u64 v[52:53], v[156:157], 0, s[10:11]
	v_add_co_u32_e32 v54, vcc, 0x26aec000, v52
	s_nop 1
	v_addc_co_u32_e32 v55, vcc, 0, v53, vcc
	global_load_dwordx4 v[138:141], v[54:55], off
	s_and_saveexec_b64 s[4:5], s[0:1]
	s_cbranch_execz .Lgqa_B_346
	v_add_co_u32_e32 v50, vcc, 0x252fc000, v50
	s_nop 1
	v_addc_co_u32_e32 v51, vcc, 0, v51, vcc
	global_load_dwordx4 v[134:137], v[50:51], off
	s_branch .Lgqa_B_346
.Lgqa_B_346:
	s_or_b64 exec, exec, s[4:5]
	v_add_co_u32_e32 v50, vcc, 0x26aee000, v52
	s_nop 1
	v_addc_co_u32_e32 v51, vcc, 0, v53, vcc
	global_load_dwordx4 v[142:145], v[50:51], off
.Lgqa_B_ls_end:
	v_add_f32_e32 v165, v62, v165
	v_add_f32_e32 v242, v63, v64
	v_add_f32_e32 v165, v65, v165
	v_add_f32_e32 v242, v74, v242
	v_add_f32_e32 v165, v75, v165
	v_add_f32_e32 v242, v76, v242
	v_add_f32_e32 v165, v77, v165
	v_add_f32_e32 v242, v78, v242
	v_add_f32_e32 v165, v79, v165
	v_add_f32_e32 v242, v80, v242
	v_add_f32_e32 v165, v81, v165
	v_add_f32_e32 v242, v106, v242
	s_waitcnt lgkmcnt(6)
	v_mfma_f32_32x32x16_bf16 v[50:65], v[214:217], v[114:117], v[34:49]
	ds_read_b128 v[214:217], v0 offset:4704
	v_add_f32_e32 v165, v107, v165
	v_add_f32_e32 v242, v108, v242
	v_add_f32_e32 v165, v109, v165
	v_add_f32_e32 v242, v110, v242
	v_add_f32_e32 v165, v111, v165
	s_waitcnt lgkmcnt(6)
	v_mfma_f32_32x32x16_bf16 v[50:65], v[218:221], v[118:121], v[50:65]
	ds_read_b128 v[218:221], v0
	v_add_f32_e32 v242, v112, v242
	v_add_f32_e32 v165, v113, v165
	v_add_f32_e32 v242, v82, v242
	v_add_f32_e32 v165, v83, v165
	v_add_f32_e32 v242, v84, v242
	s_waitcnt lgkmcnt(6)
	v_mfma_f32_32x32x16_bf16 v[50:65], v[222:225], v[122:125], v[50:65]
	ds_read_b128 v[222:225], v0 offset:32
	v_add_f32_e32 v165, v85, v165
	v_add_f32_e32 v242, v86, v242
	v_add_f32_e32 v165, v87, v165
	v_add_f32_e32 v242, v88, v242
	v_add_f32_e32 v165, v89, v165
	s_waitcnt lgkmcnt(6)
	v_mfma_f32_32x32x16_bf16 v[50:65], v[226:229], v[126:129], v[50:65]
	ds_read_b128 v[226:229], v0 offset:64
	v_add_f32_e32 v242, v90, v242
	v_add_f32_e32 v165, v91, v165
	v_add_f32_e32 v242, v92, v242
	v_add_f32_e32 v165, v93, v165
	v_add_f32_e32 v242, v94, v242
	s_waitcnt lgkmcnt(6)
	v_mfma_f32_32x32x16_bf16 v[66:81], v[230:233], v[114:117], v[34:49]
	ds_read_b128 v[230:233], v0 offset:96
	v_add_f32_e32 v165, v95, v165
	v_add_f32_e32 v242, v96, v242
	v_add_f32_e32 v165, v97, v165
	v_add_f32_e32 v242, v166, v242
	s_waitcnt lgkmcnt(6)
	v_mfma_f32_32x32x16_bf16 v[66:81], v[234:237], v[118:121], v[66:81]
	ds_read_b128 v[234:237], v0 offset:13824
	v_add_f32_e32 v165, v167, v165
	v_add_f32_e32 v242, v168, v242
	v_add_f32_e32 v165, v169, v165
	v_add_f32_e32 v242, v170, v242
	s_waitcnt lgkmcnt(6)
	v_mfma_f32_32x32x16_bf16 v[66:81], v[238:241], v[122:125], v[66:81]
	ds_read_b128 v[238:241], v0 offset:13856
	v_add_f32_e32 v165, v171, v165
	v_add_f32_e32 v242, v172, v242
	v_add_f32_e32 v165, v173, v165
	v_add_f32_e32 v242, v174, v242
	v_max3_f32 v146, v50, v51, v52
	v_max3_f32 v146, v146, v53, v54
	s_waitcnt lgkmcnt(6)
	v_mfma_f32_32x32x16_bf16 v[66:81], v[214:217], v[126:129], v[66:81]
	ds_read_b128 v[214:217], v0 offset:13888
	v_add_f32_e32 v165, v175, v165
	v_add_f32_e32 v242, v176, v242
	v_add_f32_e32 v165, v177, v165
	v_add_f32_e32 v242, v178, v242
	v_max3_f32 v146, v146, v55, v56
	v_max3_f32 v146, v146, v57, v58
	s_waitcnt lgkmcnt(6)
	v_mfma_f32_32x32x16_bf16 v[98:113], v[218:221], v[114:117], v[34:49]
	ds_read_b128 v[218:221], v0 offset:13920
	v_add_f32_e32 v165, v179, v165
	v_add_f32_e32 v242, v191, v242
	v_add_f32_e32 v165, v192, v165
	v_add_f32_e32 v242, v193, v242
	v_max3_f32 v146, v146, v59, v60
	v_max3_f32 v146, v146, v61, v62
	s_waitcnt lgkmcnt(6)
	v_mfma_f32_32x32x16_bf16 v[98:113], v[222:225], v[118:121], v[98:113]
	ds_read_b128 v[206:209], v0 offset:36864
	v_add_f32_e32 v165, v194, v165
	v_add_f32_e32 v242, v195, v242
	v_add_f32_e32 v165, v196, v165
	v_add_f32_e32 v242, v197, v242
	v_max3_f32 v146, v146, v63, v64
	v_max3_f32 v146, v146, v65, v65
	s_waitcnt lgkmcnt(6)
	v_mfma_f32_32x32x16_bf16 v[98:113], v[226:229], v[122:125], v[98:113]
	ds_read_b128 v[210:213], v0 offset:41472
	v_add_f32_e32 v165, v198, v165
	v_add_f32_e32 v242, v199, v242
	v_add_f32_e32 v165, v200, v165
	v_add_f32_e32 v242, v201, v242
	v_max3_f32 v146, v146, v66, v67
	v_max3_f32 v146, v146, v68, v69
	s_waitcnt lgkmcnt(6)
	v_mfma_f32_32x32x16_bf16 v[98:113], v[230:233], v[126:129], v[98:113]
	ds_read_b128 v[222:225], v0 offset:36896
	v_add_f32_e32 v165, v202, v165
	v_add_f32_e32 v242, v203, v242
	v_add_f32_e32 v165, v204, v165
	v_add_f32_e32 v165, v242, v165
	v_max3_f32 v146, v146, v70, v71
	v_max3_f32 v146, v146, v72, v73
	s_waitcnt lgkmcnt(6)
	v_mfma_f32_32x32x16_bf16 v[82:97], v[234:237], v[114:117], v[34:49]
	ds_read_b128 v[226:229], v0 offset:41504
	v_max3_f32 v146, v146, v74, v75
	v_max3_f32 v146, v146, v76, v77
	s_waitcnt lgkmcnt(6)
	v_mfma_f32_32x32x16_bf16 v[82:97], v[238:241], v[118:121], v[82:97]
	ds_read_b128 v[230:233], v0 offset:36928
	v_max3_f32 v146, v146, v78, v79
	v_max3_f32 v146, v146, v80, v81
	s_waitcnt lgkmcnt(6)
	v_mfma_f32_32x32x16_bf16 v[82:97], v[214:217], v[122:125], v[82:97]
	ds_read_b128 v[234:237], v0 offset:41536
	s_waitcnt lgkmcnt(6)
	v_mfma_f32_32x32x16_bf16 v[82:97], v[218:221], v[126:129], v[82:97]
	v_max3_f32 v146, v146, v98, v99
	v_max3_f32 v146, v146, v100, v101
	v_max3_f32 v146, v146, v102, v103
	v_max3_f32 v146, v146, v104, v105
	v_max3_f32 v146, v146, v106, v107
	v_max3_f32 v146, v146, v108, v109
	v_max3_f32 v146, v146, v110, v111
	v_max3_f32 v146, v146, v112, v113
	s_nop 3
	v_max3_f32 v146, v146, v82, v83
	v_max3_f32 v146, v146, v84, v85
	v_max3_f32 v146, v146, v86, v87
	v_max3_f32 v146, v146, v88, v89
	v_max3_f32 v146, v146, v90, v91
	v_max3_f32 v146, v146, v92, v93
	v_max3_f32 v146, v146, v94, v95
	v_max3_f32 v146, v146, v96, v97
	v_mov_b32_e32 v147, v146
	s_nop 1
	v_permlane32_swap_b32_e32 v146, v147
	v_max_f32_e32 v147, v147, v147
	v_max_f32_e32 v146, v146, v146
	v_max_f32_e32 v146, v146, v147
	v_cmp_lt_f32_e32 vcc, s50, v146
	s_cbranch_vccz .LBB0_350
	v_max_f32_e32 v146, v146, v146
	v_max_f32_e32 v146, 0, v146
	v_exp_f32_e64 v148, -v146
	v_pk_add_f32 v[98:99], v[98:99], v[146:147] op_sel_hi:[1,0] neg_lo:[0,1] neg_hi:[0,1]
	v_pk_add_f32 v[66:67], v[66:67], v[146:147] op_sel_hi:[1,0] neg_lo:[0,1] neg_hi:[0,1]
	v_pk_add_f32 v[50:51], v[50:51], v[146:147] op_sel_hi:[1,0] neg_lo:[0,1] neg_hi:[0,1]
	v_mul_f32_e32 v165, v165, v148
	v_pk_mul_f32 v[16:17], v[16:17], v[148:149] op_sel_hi:[1,0]
	v_pk_mul_f32 v[14:15], v[14:15], v[148:149] op_sel_hi:[1,0]
	v_pk_mul_f32 v[12:13], v[12:13], v[148:149] op_sel_hi:[1,0]
	v_pk_mul_f32 v[10:11], v[10:11], v[148:149] op_sel_hi:[1,0]
	v_pk_mul_f32 v[8:9], v[8:9], v[148:149] op_sel_hi:[1,0]
	v_pk_mul_f32 v[6:7], v[6:7], v[148:149] op_sel_hi:[1,0]
	v_pk_mul_f32 v[4:5], v[4:5], v[148:149] op_sel_hi:[1,0]
	v_pk_mul_f32 v[2:3], v[2:3], v[148:149] op_sel_hi:[1,0]
	v_pk_mul_f32 v[32:33], v[32:33], v[148:149] op_sel_hi:[1,0]
	v_pk_mul_f32 v[30:31], v[30:31], v[148:149] op_sel_hi:[1,0]
	v_pk_mul_f32 v[28:29], v[28:29], v[148:149] op_sel_hi:[1,0]
	v_pk_mul_f32 v[26:27], v[26:27], v[148:149] op_sel_hi:[1,0]
	v_pk_mul_f32 v[24:25], v[24:25], v[148:149] op_sel_hi:[1,0]
	v_pk_mul_f32 v[22:23], v[22:23], v[148:149] op_sel_hi:[1,0]
	v_pk_mul_f32 v[20:21], v[20:21], v[148:149] op_sel_hi:[1,0]
	v_pk_mul_f32 v[18:19], v[18:19], v[148:149] op_sel_hi:[1,0]
	v_pk_add_f32 v[82:83], v[82:83], v[146:147] op_sel_hi:[1,0] neg_lo:[0,1] neg_hi:[0,1]
	v_pk_add_f32 v[100:101], v[100:101], v[146:147] op_sel_hi:[1,0] neg_lo:[0,1] neg_hi:[0,1]
	v_pk_add_f32 v[68:69], v[68:69], v[146:147] op_sel_hi:[1,0] neg_lo:[0,1] neg_hi:[0,1]
	v_pk_add_f32 v[52:53], v[52:53], v[146:147] op_sel_hi:[1,0] neg_lo:[0,1] neg_hi:[0,1]
	v_pk_add_f32 v[84:85], v[84:85], v[146:147] op_sel_hi:[1,0] neg_lo:[0,1] neg_hi:[0,1]
	v_pk_add_f32 v[102:103], v[102:103], v[146:147] op_sel_hi:[1,0] neg_lo:[0,1] neg_hi:[0,1]
	v_pk_add_f32 v[70:71], v[70:71], v[146:147] op_sel_hi:[1,0] neg_lo:[0,1] neg_hi:[0,1]
	v_pk_add_f32 v[54:55], v[54:55], v[146:147] op_sel_hi:[1,0] neg_lo:[0,1] neg_hi:[0,1]
	v_pk_add_f32 v[86:87], v[86:87], v[146:147] op_sel_hi:[1,0] neg_lo:[0,1] neg_hi:[0,1]
	v_pk_add_f32 v[104:105], v[104:105], v[146:147] op_sel_hi:[1,0] neg_lo:[0,1] neg_hi:[0,1]
	v_pk_add_f32 v[72:73], v[72:73], v[146:147] op_sel_hi:[1,0] neg_lo:[0,1] neg_hi:[0,1]
	v_pk_add_f32 v[56:57], v[56:57], v[146:147] op_sel_hi:[1,0] neg_lo:[0,1] neg_hi:[0,1]
	v_pk_add_f32 v[88:89], v[88:89], v[146:147] op_sel_hi:[1,0] neg_lo:[0,1] neg_hi:[0,1]
	v_pk_add_f32 v[106:107], v[106:107], v[146:147] op_sel_hi:[1,0] neg_lo:[0,1] neg_hi:[0,1]
	v_pk_add_f32 v[74:75], v[74:75], v[146:147] op_sel_hi:[1,0] neg_lo:[0,1] neg_hi:[0,1]
	v_pk_add_f32 v[58:59], v[58:59], v[146:147] op_sel_hi:[1,0] neg_lo:[0,1] neg_hi:[0,1]
	v_pk_add_f32 v[90:91], v[90:91], v[146:147] op_sel_hi:[1,0] neg_lo:[0,1] neg_hi:[0,1]
	v_pk_add_f32 v[108:109], v[108:109], v[146:147] op_sel_hi:[1,0] neg_lo:[0,1] neg_hi:[0,1]
	v_pk_add_f32 v[76:77], v[76:77], v[146:147] op_sel_hi:[1,0] neg_lo:[0,1] neg_hi:[0,1]
	v_pk_add_f32 v[60:61], v[60:61], v[146:147] op_sel_hi:[1,0] neg_lo:[0,1] neg_hi:[0,1]
	v_pk_add_f32 v[92:93], v[92:93], v[146:147] op_sel_hi:[1,0] neg_lo:[0,1] neg_hi:[0,1]
	v_pk_add_f32 v[110:111], v[110:111], v[146:147] op_sel_hi:[1,0] neg_lo:[0,1] neg_hi:[0,1]
	v_pk_add_f32 v[78:79], v[78:79], v[146:147] op_sel_hi:[1,0] neg_lo:[0,1] neg_hi:[0,1]
	v_pk_add_f32 v[62:63], v[62:63], v[146:147] op_sel_hi:[1,0] neg_lo:[0,1] neg_hi:[0,1]
	v_pk_add_f32 v[94:95], v[94:95], v[146:147] op_sel_hi:[1,0] neg_lo:[0,1] neg_hi:[0,1]
	v_pk_add_f32 v[112:113], v[112:113], v[146:147] op_sel_hi:[1,0] neg_lo:[0,1] neg_hi:[0,1]
	v_pk_add_f32 v[80:81], v[80:81], v[146:147] op_sel_hi:[1,0] neg_lo:[0,1] neg_hi:[0,1]
	v_pk_add_f32 v[64:65], v[64:65], v[146:147] op_sel_hi:[1,0] neg_lo:[0,1] neg_hi:[0,1]
	v_pk_add_f32 v[96:97], v[96:97], v[146:147] op_sel_hi:[1,0] neg_lo:[0,1] neg_hi:[0,1]
	v_sub_f32_e32 v49, v49, v146
	v_sub_f32_e32 v48, v48, v146
	v_sub_f32_e32 v47, v47, v146
	v_sub_f32_e32 v46, v46, v146
	v_sub_f32_e32 v45, v45, v146
	v_sub_f32_e32 v44, v44, v146
	v_sub_f32_e32 v43, v43, v146
	v_sub_f32_e32 v42, v42, v146
	v_sub_f32_e32 v41, v41, v146
	v_sub_f32_e32 v40, v40, v146
	v_sub_f32_e32 v39, v39, v146
	v_sub_f32_e32 v38, v38, v146
	v_sub_f32_e32 v37, v37, v146
	v_sub_f32_e32 v36, v36, v146
	v_sub_f32_e32 v35, v35, v146
	v_sub_f32_e32 v34, v34, v146
; #define GLOAD(kt_, KR, VR) do { _Pragma("unroll") for (int i = 0; i < KCH; ++i) if (krow_[i] < 64) KR[i] = *(const u32x4*)(kbase + (size_t)((kt_) * 64 + krow_[i]) * HK * DQ + kcol_[i]); \
;     VR = *(const u32x4*)(vbase + (size_t)(kt_) * 4096 + vrow * 64 + vcol); } while (0)
; #define LSTORE(buf_, KR, VR) do { _Pragma("unroll") for (int i = 0; i < KCH; ++i) if (krow_[i] < 64) *(u32x4*)(sK + (buf_) * 64 * KROW + krow_[i] * KROW + kcol_[i]) = KR[i]; \
;     u16* d_ = sV + (buf_) * 64 * VROW + vrow * VROW + (vcol >> 4) * 16 + ((vcol >> 3) & 1) * 4; u32x2 lo_ = {VR.x, VR.y}, hi_ = {VR.z, VR.w}; *(u32x2*)d_ = lo_; *(u32x2*)(d_ + 8) = hi_; } while (0)
; #define PP_BAR asm volatile("s_waitcnt lgkmcnt(0)\n\ts_barrier" ::: "memory")
; template <int DQ>
; DI void attn_dense_item(const u16* __restrict__ Q, int qh, const u16* __restrict__ Kp, int HK, int kh, const u16* __restrict__ Vt,
;                         int S, int s0, int qblk, u16* __restrict__ MER, int ocol, float* __restrict__ ssqo, int slot, unsigned char* smem) {
;     ...
;   s16x8 pb[8];
;   for (int kt = 0; kt < nkt; kt += 2) {
;     const int sb = (kt & 2), nb = sb ^ 2;
;     TILE_X2(sb, kt == 0); TILE_Y2(sb);
;     if (kt + 2 < nkt) { LSTORE(nb, krA, vrA); LSTORE(nb + 1, krB, vrB); }
;     if (kt + 4 < nkt) { GLOAD(kt + 4, krA, vrA); GLOAD(kt + 5, krB, vrB); }
;     PP_BAR;
.LBB0_350:
	v_exp_f32_e32 v166, v98
	v_exp_f32_e32 v167, v99
	v_exp_f32_e32 v168, v100
	v_exp_f32_e32 v169, v101
	v_exp_f32_e32 v170, v102
	v_exp_f32_e32 v171, v103
	v_exp_f32_e32 v172, v104
	v_exp_f32_e32 v173, v105
	v_cvt_pk_bf16_f32 v146, v166, v167
	v_cvt_pk_bf16_f32 v147, v168, v169
	v_cvt_pk_bf16_f32 v148, v170, v171
	v_cvt_pk_bf16_f32 v149, v172, v173
	v_exp_f32_e32 v106, v106
	v_exp_f32_e32 v107, v107
	s_waitcnt lgkmcnt(5)
	v_mfma_f32_32x32x16_bf16 v[18:33], v[206:209], v[146:149], v[18:33]
	ds_read_b128 v[206:209], v0 offset:36960
	v_exp_f32_e32 v108, v108
	v_exp_f32_e32 v109, v109
	v_exp_f32_e32 v110, v110
	v_exp_f32_e32 v111, v111
	v_exp_f32_e32 v112, v112
	v_exp_f32_e32 v113, v113
	s_waitcnt lgkmcnt(5)
	v_mfma_f32_32x32x16_bf16 v[2:17], v[210:213], v[146:149], v[2:17]
	ds_read_b128 v[210:213], v0 offset:41568
	v_cvt_pk_bf16_f32 v102, v106, v107
	v_cvt_pk_bf16_f32 v103, v108, v109
	v_cvt_pk_bf16_f32 v104, v110, v111
	v_cvt_pk_bf16_f32 v105, v112, v113
	v_exp_f32_e32 v174, v66
	v_exp_f32_e32 v175, v67
	s_waitcnt lgkmcnt(5)
	v_mfma_f32_32x32x16_bf16 v[18:33], v[222:225], v[102:105], v[18:33]
	ds_read_b128 v[222:225], v0 offset:46080
	v_exp_f32_e32 v176, v68
	v_exp_f32_e32 v177, v69
	v_exp_f32_e32 v178, v70
	v_exp_f32_e32 v179, v71
	v_exp_f32_e32 v191, v72
	v_exp_f32_e32 v192, v73
	v_cvt_pk_bf16_f32 v98, v174, v175
	s_waitcnt lgkmcnt(5)
	v_mfma_f32_32x32x16_bf16 v[2:17], v[226:229], v[102:105], v[2:17]
	ds_read_b128 v[226:229], v0 offset:50688
	v_cvt_pk_bf16_f32 v99, v176, v177
	v_cvt_pk_bf16_f32 v100, v178, v179
	v_cvt_pk_bf16_f32 v101, v191, v192
	v_exp_f32_e32 v74, v74
	v_exp_f32_e32 v75, v75
	v_exp_f32_e32 v76, v76
	s_waitcnt lgkmcnt(5)
	v_mfma_f32_32x32x16_bf16 v[18:33], v[230:233], v[98:101], v[18:33]
	ds_read_b128 v[230:233], v0 offset:46112
	v_exp_f32_e32 v77, v77
	v_exp_f32_e32 v78, v78
	v_exp_f32_e32 v79, v79
	v_exp_f32_e32 v80, v80
	v_exp_f32_e32 v81, v81
	v_cvt_pk_bf16_f32 v70, v74, v75
	s_waitcnt lgkmcnt(5)
	v_mfma_f32_32x32x16_bf16 v[2:17], v[234:237], v[98:101], v[2:17]
	ds_read_b128 v[234:237], v0 offset:50720
	v_cvt_pk_bf16_f32 v71, v76, v77
	v_cvt_pk_bf16_f32 v72, v78, v79
	v_cvt_pk_bf16_f32 v73, v80, v81
	v_exp_f32_e32 v193, v50
	v_exp_f32_e32 v194, v51
	v_exp_f32_e32 v195, v52
	s_waitcnt lgkmcnt(5)
	v_mfma_f32_32x32x16_bf16 v[18:33], v[206:209], v[70:73], v[18:33]
	ds_read_b128 v[206:209], v0 offset:46144
	v_exp_f32_e32 v196, v53
	v_exp_f32_e32 v197, v54
	v_exp_f32_e32 v198, v55
	v_exp_f32_e32 v199, v56
	v_exp_f32_e32 v200, v57
	v_cvt_pk_bf16_f32 v66, v193, v194
	s_waitcnt lgkmcnt(5)
	v_mfma_f32_32x32x16_bf16 v[2:17], v[210:213], v[70:73], v[2:17]
	ds_read_b128 v[210:213], v0 offset:50752
	v_cvt_pk_bf16_f32 v67, v195, v196
	v_cvt_pk_bf16_f32 v68, v197, v198
	v_cvt_pk_bf16_f32 v69, v199, v200
	v_exp_f32_e32 v201, v58
	v_exp_f32_e32 v202, v59
	v_exp_f32_e32 v203, v60
	s_waitcnt lgkmcnt(5)
	v_mfma_f32_32x32x16_bf16 v[18:33], v[222:225], v[66:69], v[18:33]
	ds_read_b128 v[222:225], v0 offset:46176
	v_exp_f32_e32 v204, v61
	v_exp_f32_e32 v62, v62
	v_exp_f32_e32 v63, v63
	v_exp_f32_e32 v64, v64
	v_exp_f32_e32 v65, v65
	v_cvt_pk_bf16_f32 v58, v201, v202
	s_waitcnt lgkmcnt(5)
	v_mfma_f32_32x32x16_bf16 v[2:17], v[226:229], v[66:69], v[2:17]
	ds_read_b128 v[226:229], v0 offset:50784
	v_cvt_pk_bf16_f32 v59, v203, v204
	v_cvt_pk_bf16_f32 v60, v62, v63
	v_cvt_pk_bf16_f32 v61, v64, v65
	v_exp_f32_e32 v82, v82
	v_exp_f32_e32 v83, v83
	v_exp_f32_e32 v84, v84
	s_waitcnt lgkmcnt(5)
	v_mfma_f32_32x32x16_bf16 v[18:33], v[230:233], v[58:61], v[18:33]
	v_exp_f32_e32 v85, v85
	v_exp_f32_e32 v86, v86
	v_exp_f32_e32 v87, v87
	v_exp_f32_e32 v88, v88
	v_exp_f32_e32 v89, v89
	v_cvt_pk_bf16_f32 v54, v82, v83
	s_waitcnt lgkmcnt(4)
	v_mfma_f32_32x32x16_bf16 v[2:17], v[234:237], v[58:61], v[2:17]
	v_cvt_pk_bf16_f32 v55, v84, v85
	v_cvt_pk_bf16_f32 v56, v86, v87
	v_cvt_pk_bf16_f32 v57, v88, v89
	v_exp_f32_e32 v90, v90
	v_exp_f32_e32 v91, v91
	v_exp_f32_e32 v92, v92
	s_waitcnt lgkmcnt(3)
	v_mfma_f32_32x32x16_bf16 v[18:33], v[206:209], v[54:57], v[18:33]
	v_exp_f32_e32 v93, v93
	v_exp_f32_e32 v94, v94
	v_exp_f32_e32 v95, v95
	v_exp_f32_e32 v96, v96
	v_exp_f32_e32 v97, v97
	v_cvt_pk_bf16_f32 v50, v90, v91
	s_waitcnt lgkmcnt(2)
	v_mfma_f32_32x32x16_bf16 v[2:17], v[210:213], v[54:57], v[2:17]
	v_cvt_pk_bf16_f32 v51, v92, v93
	v_cvt_pk_bf16_f32 v52, v94, v95
	v_cvt_pk_bf16_f32 v53, v96, v97
	s_add_i32 s13, s12, -2
	s_cmp_ge_u32 s13, s23
	s_waitcnt lgkmcnt(1)
	v_mfma_f32_32x32x16_bf16 v[18:33], v[222:225], v[50:53], v[18:33]
	s_waitcnt lgkmcnt(0)
	v_mfma_f32_32x32x16_bf16 v[2:17], v[226:229], v[50:53], v[2:17]
	s_branch .LBB0_347

; __global__ void __launch_bounds__(512, 2) fwd_mega(Params p) {
;     ...
;     if (ph + 1 < p.ph_hi) cg::this_grid().sync();
.LBB0_1222:
	v_readlane_b32 s6, v250, 0
	s_load_dword s11, s[68:69], 0x0
	s_add_u32 s4, s90, 0x410000
	s_addc_u32 s5, s91, 0
	s_waitcnt lgkmcnt(0)
	s_cmp_eq_u32 s6, 1
	s_cbranch_scc1 .Lgs_first
	s_cmp_eq_u32 s11, 0x100
	s_cbranch_scc0 .Lgs_orig
	buffer_wbl2 sc1
	v_readlane_b32 s7, v248, 2
	s_nop 3
	s_and_b32 s7, s7, 7
	s_lshl_b32 s7, s7, 8
	v_mov_b32_e32 v2, s7
	v_mov_b32_e32 v3, 1
	s_waitcnt vmcnt(0)
	global_atomic_add v0, v2, v3, s[4:5] sc0
	s_waitcnt vmcnt(0)
	v_readfirstlane_b32 s8, v0
	s_nop 3
	s_lshr_b32 s9, s8, 5
	s_and_b32 s10, s8, 31
	s_add_u32 s7, s7, 0x1000
	s_cmp_eq_u32 s10, 31
	s_cbranch_scc0 .Lgs_wait_group
	v_mov_b32_e32 v2, 0x2000
	global_atomic_add v0, v2, v3, s[4:5] sc0
	s_waitcnt vmcnt(0)
	v_readfirstlane_b32 s8, v0
	s_nop 3
	s_lshr_b32 s10, s8, 3
	s_and_b32 s11, s8, 7
	v_mov_b32_e32 v2, 0x2100
	s_cmp_eq_u32 s11, 7
	s_cbranch_scc0 .Lgs_spin_top
	global_atomic_add v2, v3, s[4:5]
	s_branch .Lgs_release_group
.Lgs_spin_top:
	s_sleep 1
	global_load_dword v0, v2, s[4:5] sc1
	s_waitcnt vmcnt(0)
	v_readfirstlane_b32 s8, v0
	s_nop 3
	s_cmp_eq_u32 s8, s10
	s_cbranch_scc1 .Lgs_spin_top
.Lgs_release_group:
	v_mov_b32_e32 v2, s7
	global_atomic_add v2, v3, s[4:5]
	s_branch .Lgs_acquire
.Lgs_wait_group:
	v_mov_b32_e32 v2, s7
.Lgs_spin_group:
	s_sleep 1
	global_load_dword v0, v2, s[4:5] sc1
	s_waitcnt vmcnt(0)
	v_readfirstlane_b32 s8, v0
	s_nop 3
	s_cmp_eq_u32 s8, s9
	s_cbranch_scc1 .Lgs_spin_group
.Lgs_acquire:
	s_waitcnt vmcnt(0)
	s_branch .Lgs_to_inv
.Lgs_first:
	v_mov_b32_e32 v3, 0
	v_mov_b32_e32 v2, 0x0
	global_store_dword v2, v3, s[4:5]
	v_mov_b32_e32 v2, 0x100
	global_store_dword v2, v3, s[4:5]
	v_mov_b32_e32 v2, 0x200
	global_store_dword v2, v3, s[4:5]
	v_mov_b32_e32 v2, 0x300
	global_store_dword v2, v3, s[4:5]
	v_mov_b32_e32 v2, 0x400
	global_store_dword v2, v3, s[4:5]
	v_mov_b32_e32 v2, 0x500
	global_store_dword v2, v3, s[4:5]
	v_mov_b32_e32 v2, 0x600
	global_store_dword v2, v3, s[4:5]
	v_mov_b32_e32 v2, 0x700
	global_store_dword v2, v3, s[4:5]
	v_mov_b32_e32 v2, 0x1000
	global_store_dword v2, v3, s[4:5]
	v_mov_b32_e32 v2, 0x1100
	global_store_dword v2, v3, s[4:5]
	v_mov_b32_e32 v2, 0x1200
	global_store_dword v2, v3, s[4:5]
	v_mov_b32_e32 v2, 0x1300
	global_store_dword v2, v3, s[4:5]
	v_mov_b32_e32 v2, 0x1400
	global_store_dword v2, v3, s[4:5]
	v_mov_b32_e32 v2, 0x1500
	global_store_dword v2, v3, s[4:5]
	v_mov_b32_e32 v2, 0x1600
	global_store_dword v2, v3, s[4:5]
	v_mov_b32_e32 v2, 0x1700
	global_store_dword v2, v3, s[4:5]
	v_mov_b32_e32 v2, 0x2000
	global_store_dword v2, v3, s[4:5]
	v_mov_b32_e32 v2, 0x2100
	global_store_dword v2, v3, s[4:5]

; __global__ void __launch_bounds__(512, 2) fwd_mega(Params p) {
;     ...
;     if (ph + 1 < p.ph_hi) cg::this_grid().sync();
.Lgs_to_inv:
	s_getpc_b64 s[98:99]
